# grid barrier between attention and the RWKV output phase replaced by a scan-done counter (release by the 32 scan workgroups, acquire by each workgroup when its attention queue is empty)
# baseline (speedup 1.0000x reference)
; __device__ void phase_scan(const Params& p, int bid, int nb) {
;     ...
;     for (int c = 0; c < 63; c += 3) {
;       loadc(b2, c + 2); __builtin_amdgcn_sched_barrier(0);
;       step(b0, c); __builtin_amdgcn_sched_barrier(0);
;       loadc(b0, c + 3); __builtin_amdgcn_sched_barrier(0);
;       step(b1, c + 1); __builtin_amdgcn_sched_barrier(0);
;       if (c + 4 < 64) loadc(b1, c + 4);
;       __builtin_amdgcn_sched_barrier(0);
;       step(b2, c + 2); __builtin_amdgcn_sched_barrier(0);
;     }
;     step(b0, 63);
;   }
.LBB0_390:
	s_or_b64 exec, exec, s[4:5]
	s_waitcnt vmcnt(0)
	s_barrier
	v_cmp_eq_u32_e32 vcc, 0, v223
	s_and_saveexec_b64 s[4:5], vcc
	s_cbranch_execz .Lscan_sig_done
	buffer_wbl2 sc1
	s_load_dwordx2 s[6:7], s[0:1], 0x138
	v_mov_b32_e32 v2, 0
	v_mov_b32_e32 v3, 1
	s_waitcnt vmcnt(0) lgkmcnt(0)
	global_atomic_add v2, v3, s[6:7] offset:4
	s_waitcnt vmcnt(0)

; __device__ __forceinline__ unsigned xb_ld(unsigned* p)              { return __hip_atomic_load(p, __ATOMIC_RELAXED, __HIP_MEMORY_SCOPE_AGENT); }
; __device__ __forceinline__ unsigned xb_add(unsigned* p, unsigned v) { return __hip_atomic_fetch_add(p, v, __ATOMIC_RELAXED, __HIP_MEMORY_SCOPE_AGENT); }
; #define XB_SPIN(cond, bar) do { unsigned _sp = 0; while (cond) { __builtin_amdgcn_s_sleep(1); \
;     if ((++_sp & 255u) == 0u) { if (xb_ld(&(bar)[XB_TMO])) break; if (_sp > XB_SPIN_CAP) { atomicAdd(&(bar)[XB_TMO], 1u); break; } } } } while (0)
; __device__ __forceinline__ void xcd_barrier(const XcdBarrier& b) {
;     asm volatile("s_waitcnt vmcnt(0)" ::: "memory");
;     __syncthreads();
;     if (threadIdx.x == 0) {
;         unsigned* bar = b.bar;
;         __builtin_amdgcn_s_waitcnt(0);
;         unsigned nloc = b.st[0], nx = b.st[1];
;         if (nloc == 0u) { xcd_barrier_complete(bar, b.x, nloc, nx); b.st[0] = nloc; b.st[1] = nx; }
;         const unsigned old = xb_add(&bar[XB_XSUB(b.x)], 1u);
;         const unsigned gen = old / nloc;
;         if (old + 1u == (gen + 1u) * nloc) {
;             __builtin_amdgcn_fence(__ATOMIC_RELEASE, "agent");
;             asm volatile("s_waitcnt vmcnt(0)" ::: "memory");
;             const unsigned og = xb_add(&bar[XB_TOP], 1u);
;             const unsigned tg = og / nx;
;             if (og + 1u == (tg + 1u) * nx) xb_add(&bar[XB_TOPGEN], 1u);
;             else XB_SPIN(xb_ld(&bar[XB_TOPGEN]) == tg, bar);
;             __builtin_amdgcn_fence(__ATOMIC_ACQUIRE, "agent");
;             xb_add(&bar[XB_XGEN(b.x)], 1u);
;             asm volatile("s_waitcnt vmcnt(0)" ::: "memory");
;         } else {
;             XB_SPIN(xb_ld(&bar[XB_XGEN(b.x)]) == gen, bar);
;             __builtin_amdgcn_fence(__ATOMIC_ACQUIRE, "agent");
;             asm volatile("s_waitcnt vmcnt(0)" ::: "memory");
;         }
;     }
;     __syncthreads();
; }
.LBB0_444:
	s_waitcnt vmcnt(0)
	s_barrier
	v_cmp_eq_u32_e32 vcc, 0, v223
	s_and_saveexec_b64 s[4:5], vcc
	s_cbranch_execz .LBB0_496
	s_load_dwordx2 s[6:7], s[0:1], 0x138
	v_mov_b32_e32 v2, 0
	s_waitcnt lgkmcnt(0)
.Lscan_poll:
	global_load_dword v3, v2, s[6:7] offset:4 sc1
	s_waitcnt vmcnt(0)
	v_cmp_gt_u32_e32 vcc, 32, v3
	s_cbranch_vccz .Lscan_ready
	s_sleep 1
	s_branch .Lscan_poll
.Lscan_ready:
	buffer_inv sc1
	s_waitcnt vmcnt(0)
